# P5 prompt chunk loop: dummy dword loads touch the cache lines of the chunk after next (pointers already advanced), loop-top wait vmcnt(11)
# baseline (speedup 1.0000x reference)
.LBB0_2540:
	s_and_b32 s6, s51, 1
	s_mul_i32 s7, s6, 0x12000
	s_mulk_i32 s6, 0x4800
	s_add_i32 s55, s6, 0
	s_add_i32 s52, s7, 0
	s_add_i32 s55, s55, 0x1a400
	v_add_u32_e32 v4, s52, v204
	s_waitcnt vmcnt(11)
	ds_write_b128 v4, v[42:45] offset:34816
	ds_write_b128 v4, v[38:41] offset:43520
	ds_write_b128 v204, v[62:65] offset:17408
	ds_write_b128 v204, v[66:69] offset:26112
	ds_write_b128 v216, v[70:73] offset:61440
	ds_write_b128 v217, v[74:77]
	ds_write_b128 v218, v[78:81]
	s_and_saveexec_b64 s[6:7], s[0:1]
	v_lshl_add_u32 v4, v116, 2, s55
	ds_write_b32 v4, v3
	s_or_b64 exec, exec, s[6:7]
	s_cmpk_eq_i32 s50, 0x100
	s_waitcnt lgkmcnt(0)
	s_barrier
	s_cbranch_scc1 .LBB0_2572
	global_load_dwordx4 v[42:45], v[206:207], off
	global_load_dwordx4 v[38:41], v[232:233], off
	global_load_dwordx4 v[62:65], v[208:209], off
	global_load_dwordx4 v[66:69], v[234:235], off
	global_load_dwordx4 v[78:81], v[210:211], off nt
	global_load_dwordx4 v[70:73], v[212:213], off
	global_load_dwordx4 v[74:77], v[214:215], off
	s_and_saveexec_b64 s[6:7], s[0:1]
	global_load_dword v3, v[106:107], off
	s_or_b64 exec, exec, s[6:7]
	v_lshl_add_u64 v[232:233], v[232:233], 0, s[36:37]
	v_lshl_add_u64 v[234:235], v[234:235], 0, s[36:37]
	v_lshl_add_u64 v[206:207], v[206:207], 0, s[36:37]
	v_lshl_add_u64 v[208:209], v[208:209], 0, s[36:37]
	v_lshl_add_u64 v[210:211], v[210:211], 0, s[36:37]
	v_lshl_add_u64 v[212:213], v[212:213], 0, s[36:37]
	v_lshl_add_u64 v[214:215], v[214:215], 0, s[36:37]
	global_load_dword v240, v[206:207], off
	global_load_dword v240, v[232:233], off
	global_load_dword v240, v[208:209], off
	global_load_dword v240, v[234:235], off
	global_load_dword v240, v[210:211], off
	global_load_dword v240, v[212:213], off
	global_load_dword v240, v[214:215], off

	.amdhsa_kernel _Z4mega6Params
		.amdhsa_group_segment_fixed_size 0
		.amdhsa_private_segment_fixed_size 0
		.amdhsa_kernarg_size 480
		.amdhsa_user_sgpr_count 2
		.amdhsa_user_sgpr_dispatch_ptr 0
		.amdhsa_user_sgpr_queue_ptr 0
		.amdhsa_user_sgpr_kernarg_segment_ptr 1
		.amdhsa_user_sgpr_dispatch_id 0
		.amdhsa_user_sgpr_kernarg_preload_length 0
		.amdhsa_user_sgpr_kernarg_preload_offset 0
		.amdhsa_user_sgpr_private_segment_size 0
		.amdhsa_uses_dynamic_stack 0
		.amdhsa_enable_private_segment 0
		.amdhsa_system_sgpr_workgroup_id_x 1
		.amdhsa_system_sgpr_workgroup_id_y 0
		.amdhsa_system_sgpr_workgroup_id_z 0
		.amdhsa_system_sgpr_workgroup_info 0
		.amdhsa_system_vgpr_workitem_id 2
		.amdhsa_next_free_vgpr 248
		.amdhsa_next_free_sgpr 100
		.amdhsa_accum_offset 248
		.amdhsa_reserve_vcc 1
		.amdhsa_float_round_mode_32 0
		.amdhsa_float_round_mode_16_64 0
		.amdhsa_float_denorm_mode_32 3
		.amdhsa_float_denorm_mode_16_64 3
		.amdhsa_dx10_clamp 1
		.amdhsa_ieee_mode 1
		.amdhsa_fp16_overflow 0
		.amdhsa_tg_split 0
		.amdhsa_exception_fp_ieee_invalid_op 0
		.amdhsa_exception_fp_denorm_src 0
		.amdhsa_exception_fp_ieee_div_zero 0
		.amdhsa_exception_fp_ieee_overflow 0
		.amdhsa_exception_fp_ieee_underflow 0
		.amdhsa_exception_fp_ieee_inexact 0
		.amdhsa_exception_int_div_zero 0
	.end_amdhsa_kernel

amdhsa.kernels:
  - .agpr_count:     0
    .args:
      - .offset:         0
        .size:           224
        .value_kind:     by_value
      - .offset:         224
        .size:           4
        .value_kind:     hidden_block_count_x
      - .offset:         228
        .size:           4
        .value_kind:     hidden_block_count_y
      - .offset:         232
        .size:           4
        .value_kind:     hidden_block_count_z
      - .offset:         236
        .size:           2
        .value_kind:     hidden_group_size_x
      - .offset:         238
        .size:           2
        .value_kind:     hidden_group_size_y
      - .offset:         240
        .size:           2
        .value_kind:     hidden_group_size_z
      - .offset:         242
        .size:           2
        .value_kind:     hidden_remainder_x
      - .offset:         244
        .size:           2
        .value_kind:     hidden_remainder_y
      - .offset:         246
        .size:           2
        .value_kind:     hidden_remainder_z
      - .offset:         264
        .size:           8
        .value_kind:     hidden_global_offset_x
      - .offset:         272
        .size:           8
        .value_kind:     hidden_global_offset_y
      - .offset:         280
        .size:           8
        .value_kind:     hidden_global_offset_z
      - .offset:         288
        .size:           2
        .value_kind:     hidden_grid_dims
      - .offset:         312
        .size:           8
        .value_kind:     hidden_multigrid_sync_arg
      - .offset:         344
        .size:           4
        .value_kind:     hidden_dynamic_lds_size
    .group_segment_fixed_size: 0
    .kernarg_segment_align: 8
    .kernarg_segment_size: 480
    .language:       OpenCL C
    .language_version:
      - 2
      - 0
    .max_flat_workgroup_size: 512
    .name:           _Z4mega6Params
    .private_segment_fixed_size: 0
    .sgpr_count:     106
    .sgpr_spill_count: 56
    .symbol:         _Z4mega6Params.kd
    .uniform_work_group_size: 1
    .uses_dynamic_stack: false
    .vgpr_count:     248
    .vgpr_spill_count: 0
    .wavefront_size: 64
